# FFT spectrum stage remapped to even positions only (all lanes active, 8 passes instead of 16); scan staging loads use running addresses
# speedup vs baseline: 1.0312x; 1.0031x over previous
.Lscan_pro_654:
	s_or_b64 exec, exec, s[0:1]
	v_mov_b32_e32 v59, 0
	v_add_u32_e32 v0, 64, v131
	v_sub_u32_e32 v58, 0x20ff, v0
	v_or_b32_e32 v0, 0x2000, v0
	v_cndmask_b32_e64 v58, v0, v58, s[88:89]
	v_lshlrev_b64 v[60:61], 12, v[58:59]
	v_lshlrev_b64 v[62:63], 13, v[58:59]
	v_lshlrev_b64 v[66:67], 14, v[58:59]
	v_lshl_add_u64 v[78:79], v[62:63], 0, v[120:121]
	v_lshl_add_u64 v[80:81], v[66:67], 0, v[122:123]
	v_lshl_add_u64 v[82:83], v[62:63], 0, v[124:125]
	v_lshl_add_u64 v[84:85], v[60:61], 0, v[126:127]
	v_lshl_add_u64 v[86:87], v[60:61], 0, v[128:129]
	v_add_u32_e32 v0, 64, v136
	v_sub_u32_e32 v58, 0x20ff, v0
	v_or_b32_e32 v0, 0x2000, v0
	v_cndmask_b32_e64 v58, v0, v58, s[88:89]
	v_lshlrev_b64 v[60:61], 12, v[58:59]
	v_lshlrev_b64 v[62:63], 13, v[58:59]
	v_lshlrev_b64 v[66:67], 14, v[58:59]
	v_lshl_add_u64 v[88:89], v[62:63], 0, v[120:121]
	v_lshl_add_u64 v[90:91], v[66:67], 0, v[122:123]
	v_lshl_add_u64 v[92:93], v[62:63], 0, v[124:125]
	v_lshl_add_u64 v[94:95], v[60:61], 0, v[126:127]
	v_lshl_add_u64 v[96:97], v[60:61], 0, v[128:129]

.Lscan_stage_done:
	s_or_b64 exec, exec, s[16:17]
	s_movk_i32 s0, 0x106
	v_add_u32_e32 v64, 2, v101
	v_cmp_gt_u32_e64 s[14:15], s0, v101
	s_and_saveexec_b64 s[36:37], s[14:15]
	s_cbranch_execz .Lscan_load_done
	global_load_dwordx4 v[34:37], v[78:79], off
	global_load_dwordx4 v[38:41], v[80:81], off
	global_load_dwordx2 v[110:111], v[82:83], off
	global_load_dwordx2 v[112:113], v[84:85], off
	global_load_dwordx4 v[50:53], v[88:89], off
	global_load_dwordx4 v[54:57], v[90:91], off
	global_load_dwordx2 v[114:115], v[92:93], off
	global_load_dwordx2 v[116:117], v[94:95], off
	s_and_saveexec_b64 s[0:1], s[10:11]
	global_load_dwordx2 v[106:107], v[86:87], off
	global_load_dwordx2 v[108:109], v[96:97], off
	s_or_b64 exec, exec, s[0:1]
	v_readfirstlane_b32 s0, v101
	s_movk_i32 s4, 0x20
	s_cmp_eq_u32 s0, 5
	s_cselect_b32 s4, 0xffffdf20, s4
	s_cmp_lg_u32 s88, 0
	s_cselect_b32 s0, 0xffffffe0, s4
	s_ashr_i32 s1, s0, 31
	s_lshl_b64 s[4:5], s[0:1], 13
	s_lshl_b64 s[18:19], s[0:1], 14
	s_lshl_b64 s[0:1], s[0:1], 12
	v_lshl_add_u64 v[78:79], v[78:79], 0, s[4:5]
	v_lshl_add_u64 v[82:83], v[82:83], 0, s[4:5]
	v_lshl_add_u64 v[88:89], v[88:89], 0, s[4:5]
	v_lshl_add_u64 v[92:93], v[92:93], 0, s[4:5]
	v_lshl_add_u64 v[80:81], v[80:81], 0, s[18:19]
	v_lshl_add_u64 v[90:91], v[90:91], 0, s[18:19]
	v_lshl_add_u64 v[84:85], v[84:85], 0, s[0:1]
	v_lshl_add_u64 v[86:87], v[86:87], 0, s[0:1]
	v_lshl_add_u64 v[94:95], v[94:95], 0, s[0:1]
	v_lshl_add_u64 v[96:97], v[96:97], 0, s[0:1]

.LBB0_1393:
	s_sub_i32 s1, 0, s0
	v_and_b32_e32 v184, s1, v32
	ds_read2st64_b64 v[0:3], v145 offset1:8
	ds_read2st64_b64 v[4:7], v145 offset0:32 offset1:40
	ds_read2st64_b64 v[16:19], v145 offset0:64 offset1:72
	ds_read2st64_b64 v[20:23], v145 offset0:96 offset1:104
	ds_read_b64 v[126:127], v33
	ds_read_b64 v[130:131], v146
	ds_read_b64 v[112:113], v148
	ds_read_b64 v[116:117], v149
	ds_read_b64 v[136:137], v156
	ds_read_b64 v[138:139], v157
	ds_read_b64 v[118:119], v158
	ds_read_b64 v[122:123], v159
	ds_read2st64_b64 v[8:11], v145 offset0:16 offset1:24
	ds_read2st64_b64 v[12:15], v145 offset0:48 offset1:56
	ds_read2st64_b64 v[24:27], v145 offset0:80 offset1:88
	ds_read2st64_b64 v[28:31], v145 offset0:112 offset1:120
	ds_read_b64 v[132:133], v151
	ds_read_b64 v[134:135], v152
	ds_read_b64 v[114:115], v154
	ds_read_b64 v[120:121], v155
	ds_read_b64 v[140:141], v160
	ds_read_b64 v[142:143], v161
	ds_read_b64 v[124:125], v162
	ds_read_b64 v[128:129], v163
	v_and_b32_e32 v185, s1, v147
	v_lshl_add_u32 v184, v184, 3, s29
	s_waitcnt lgkmcnt(0)
	s_barrier
	v_lshl_add_u32 v196, v185, 3, s29
	ds_read_b64 v[184:185], v184
	v_and_b32_e32 v186, s1, v150
	v_and_b32_e32 v187, s1, v153
	v_lshl_add_u32 v197, v186, 3, s29
	v_lshl_add_u32 v198, v187, 3, s29
	v_pk_add_f32 v[186:187], v[0:1], v[16:17]
	v_pk_add_f32 v[188:189], v[0:1], v[16:17] neg_lo:[0,1] neg_hi:[0,1]
	v_pk_add_f32 v[0:1], v[4:5], v[20:21]
	v_pk_add_f32 v[4:5], v[4:5], v[20:21] neg_lo:[0,1] neg_hi:[0,1]
	v_pk_add_f32 v[16:17], v[126:127], v[130:131]
	v_pk_add_f32 v[126:127], v[126:127], v[130:131] neg_lo:[0,1] neg_hi:[0,1]
	v_pk_add_f32 v[20:21], v[136:137], v[138:139]
	v_pk_add_f32 v[130:131], v[136:137], v[138:139] neg_lo:[0,1] neg_hi:[0,1]
	v_pk_add_f32 v[136:137], v[2:3], v[18:19]
	v_pk_add_f32 v[2:3], v[2:3], v[18:19] neg_lo:[0,1] neg_hi:[0,1]
	v_pk_add_f32 v[18:19], v[6:7], v[22:23]
	v_pk_add_f32 v[6:7], v[6:7], v[22:23] neg_lo:[0,1] neg_hi:[0,1]
	v_pk_add_f32 v[22:23], v[112:113], v[116:117]
	v_pk_add_f32 v[112:113], v[112:113], v[116:117] neg_lo:[0,1] neg_hi:[0,1]
	v_pk_add_f32 v[116:117], v[118:119], v[122:123]
	v_pk_add_f32 v[118:119], v[118:119], v[122:123] neg_lo:[0,1] neg_hi:[0,1]
	v_pk_add_f32 v[122:123], v[8:9], v[24:25]
	v_pk_add_f32 v[138:139], v[8:9], v[24:25] neg_lo:[0,1] neg_hi:[0,1]
	v_pk_add_f32 v[24:25], v[12:13], v[28:29]
	v_pk_add_f32 v[28:29], v[12:13], v[28:29] neg_lo:[0,1] neg_hi:[0,1]
	v_pk_add_f32 v[190:191], v[132:133], v[134:135]
	v_pk_add_f32 v[132:133], v[132:133], v[134:135] neg_lo:[0,1] neg_hi:[0,1]
	v_pk_add_f32 v[134:135], v[140:141], v[142:143]
	v_pk_add_f32 v[140:141], v[140:141], v[142:143] neg_lo:[0,1] neg_hi:[0,1]
	v_pk_add_f32 v[142:143], v[10:11], v[26:27]
	v_pk_add_f32 v[10:11], v[10:11], v[26:27] neg_lo:[0,1] neg_hi:[0,1]
	v_pk_add_f32 v[26:27], v[14:15], v[30:31]
	v_pk_add_f32 v[14:15], v[14:15], v[30:31] neg_lo:[0,1] neg_hi:[0,1]
	v_pk_add_f32 v[30:31], v[114:115], v[120:121]
	v_pk_add_f32 v[114:115], v[114:115], v[120:121] neg_lo:[0,1] neg_hi:[0,1]
	v_pk_add_f32 v[120:121], v[124:125], v[128:129]
	v_pk_add_f32 v[124:125], v[124:125], v[128:129] neg_lo:[0,1] neg_hi:[0,1]
	v_pk_mul_f32 v[128:129], v[4:5], s[58:59]
	v_pk_add_f32 v[192:193], v[186:187], v[0:1] neg_lo:[0,1] neg_hi:[0,1]
	v_pk_add_f32 v[0:1], v[186:187], v[0:1]
	v_pk_add_f32 v[186:187], v[16:17], v[20:21] neg_lo:[0,1] neg_hi:[0,1]
	v_pk_add_f32 v[4:5], v[16:17], v[20:21]
	v_pk_add_f32 v[194:195], v[136:137], v[18:19] neg_lo:[0,1] neg_hi:[0,1]
	v_pk_add_f32 v[8:9], v[136:137], v[18:19]
	v_pk_mul_f32 v[18:19], v[118:119], s[58:59]
	v_pk_add_f32 v[118:119], v[22:23], v[116:117] neg_lo:[0,1] neg_hi:[0,1]
	v_pk_add_f32 v[12:13], v[22:23], v[116:117]
	v_pk_mul_f32 v[22:23], v[28:29], s[58:59]
	v_pk_add_f32 v[116:117], v[122:123], v[24:25] neg_lo:[0,1] neg_hi:[0,1]
	v_pk_add_f32 v[16:17], v[122:123], v[24:25]
	v_pk_mul_f32 v[122:123], v[140:141], s[58:59]
	v_pk_mul_f32 v[14:15], v[14:15], s[58:59]
	v_pk_mul_f32 v[130:131], v[130:131], s[58:59]
	v_pk_mul_f32 v[6:7], v[6:7], s[58:59]
	v_pk_add_f32 v[136:137], v[190:191], v[134:135] neg_lo:[0,1] neg_hi:[0,1]
	v_pk_add_f32 v[20:21], v[190:191], v[134:135]
	v_pk_add_f32 v[134:135], v[142:143], v[26:27] neg_lo:[0,1] neg_hi:[0,1]
	v_pk_add_f32 v[24:25], v[142:143], v[26:27]
	v_pk_mul_f32 v[26:27], v[124:125], s[58:59]
	v_pk_add_f32 v[124:125], v[30:31], v[120:121] neg_lo:[0,1] neg_hi:[0,1]
	v_pk_add_f32 v[28:29], v[30:31], v[120:121]
	v_pk_add_f32 v[30:31], v[188:189], v[128:129] op_sel:[0,1] op_sel_hi:[1,0]
	v_pk_add_f32 v[120:121], v[188:189], v[128:129] op_sel:[0,1] op_sel_hi:[1,0] neg_lo:[0,1] neg_hi:[0,1]
	v_pk_add_f32 v[142:143], v[112:113], v[18:19] op_sel:[0,1] op_sel_hi:[1,0]
	v_pk_add_f32 v[18:19], v[112:113], v[18:19] op_sel:[0,1] op_sel_hi:[1,0] neg_lo:[0,1] neg_hi:[0,1]
	v_pk_add_f32 v[112:113], v[138:139], v[22:23] op_sel:[0,1] op_sel_hi:[1,0]
	v_pk_add_f32 v[138:139], v[138:139], v[22:23] op_sel:[0,1] op_sel_hi:[1,0] neg_lo:[0,1] neg_hi:[0,1]
	v_pk_add_f32 v[22:23], v[132:133], v[122:123] op_sel:[0,1] op_sel_hi:[1,0]
	v_pk_add_f32 v[122:123], v[132:133], v[122:123] op_sel:[0,1] op_sel_hi:[1,0] neg_lo:[0,1] neg_hi:[0,1]
	v_pk_add_f32 v[132:133], v[10:11], v[14:15] op_sel:[0,1] op_sel_hi:[1,0]
	v_pk_add_f32 v[188:189], v[10:11], v[14:15] op_sel:[0,1] op_sel_hi:[1,0] neg_lo:[0,1] neg_hi:[0,1]
	s_waitcnt lgkmcnt(0)
	v_xor_b32_e32 v10, 0x80000000, v185
	v_mov_b32_e32 v11, v185
	v_pk_add_f32 v[128:129], v[126:127], v[130:131] op_sel:[0,1] op_sel_hi:[1,0]
	v_pk_add_f32 v[126:127], v[126:127], v[130:131] op_sel:[0,1] op_sel_hi:[1,0] neg_lo:[0,1] neg_hi:[0,1]
	v_pk_add_f32 v[130:131], v[2:3], v[6:7] op_sel:[0,1] op_sel_hi:[1,0]
	v_pk_add_f32 v[140:141], v[2:3], v[6:7] op_sel:[0,1] op_sel_hi:[1,0] neg_lo:[0,1] neg_hi:[0,1]
	v_pk_mul_f32 v[2:3], v[184:185], v[10:11] op_sel:[1,0] op_sel_hi:[0,1]
	v_pk_add_f32 v[190:191], v[114:115], v[26:27] op_sel:[0,1] op_sel_hi:[1,0]
	v_pk_add_f32 v[114:115], v[114:115], v[26:27] op_sel:[0,1] op_sel_hi:[1,0] neg_lo:[0,1] neg_hi:[0,1]
	v_pk_mul_f32 v[6:7], v[10:11], v[30:31] op_sel:[0,1] op_sel_hi:[1,0]
	v_pk_mul_f32 v[14:15], v[10:11], v[128:129] op_sel:[0,1] op_sel_hi:[1,0]
	v_pk_fma_f32 v[26:27], v[184:185], v[184:185], v[2:3] op_sel_hi:[1,0,1]
	v_pk_fma_f32 v[2:3], v[184:185], v[30:31], v[6:7] op_sel_hi:[0,1,1]
	v_pk_fma_f32 v[6:7], v[184:185], v[128:129], v[14:15] op_sel_hi:[0,1,1]
	v_pk_mul_f32 v[10:11], v[10:11], v[26:27] op_sel:[0,1] op_sel_hi:[1,0]
	v_xor_b32_e32 v14, 0x80000000, v27
	v_mov_b32_e32 v15, v27
	ds_write_b128 v180, v[0:3]
	ds_write_b128 v164, v[4:7]
	v_pk_fma_f32 v[6:7], v[184:185], v[26:27], v[10:11] op_sel_hi:[0,1,1]
	v_pk_mul_f32 v[2:3], v[14:15], v[186:187] op_sel:[0,1] op_sel_hi:[1,0]
	v_xor_b32_e32 v10, 0x80000000, v7
	v_mov_b32_e32 v11, v7
	v_pk_mul_f32 v[0:1], v[14:15], v[192:193] op_sel:[0,1] op_sel_hi:[1,0]
	v_pk_fma_f32 v[4:5], v[26:27], v[186:187], v[2:3] op_sel_hi:[0,1,1]
	v_pk_mul_f32 v[2:3], v[120:121], v[10:11] op_sel:[1,0] op_sel_hi:[0,1]
	v_pk_fma_f32 v[0:1], v[26:27], v[192:193], v[0:1] op_sel_hi:[0,1,1]
	v_pk_mul_f32 v[10:11], v[10:11], v[126:127] op_sel:[0,1] op_sel_hi:[1,0]
	v_pk_fma_f32 v[2:3], v[120:121], v[6:7], v[2:3] op_sel_hi:[1,0,1]
	v_pk_fma_f32 v[6:7], v[6:7], v[126:127], v[10:11] op_sel_hi:[0,1,1]
	ds_write_b128 v180, v[0:3] offset:16
	ds_write_b128 v164, v[4:7] offset:16
	ds_read_b64 v[0:1], v196
	s_lshl_b32 s0, s0, 2
	s_cmpk_gt_i32 s0, 0x400
	s_waitcnt lgkmcnt(0)
	v_xor_b32_e32 v2, 0x80000000, v1
	v_mov_b32_e32 v3, v1
	v_pk_mul_f32 v[4:5], v[0:1], v[2:3] op_sel:[1,0] op_sel_hi:[0,1]
	v_pk_mul_f32 v[6:7], v[2:3], v[130:131] op_sel:[0,1] op_sel_hi:[1,0]
	v_pk_fma_f32 v[4:5], v[0:1], v[0:1], v[4:5] op_sel_hi:[1,0,1]
	v_pk_mul_f32 v[14:15], v[2:3], v[142:143] op_sel:[0,1] op_sel_hi:[1,0]
	v_pk_fma_f32 v[10:11], v[0:1], v[130:131], v[6:7] op_sel_hi:[0,1,1]
	v_pk_mul_f32 v[2:3], v[2:3], v[4:5] op_sel:[0,1] op_sel_hi:[1,0]
	v_pk_fma_f32 v[14:15], v[0:1], v[142:143], v[14:15] op_sel_hi:[0,1,1]
	v_xor_b32_e32 v6, 0x80000000, v5
	v_mov_b32_e32 v7, v5
	ds_write_b128 v165, v[8:11]
	ds_write_b128 v166, v[12:15]
	v_pk_fma_f32 v[8:9], v[0:1], v[4:5], v[2:3] op_sel_hi:[0,1,1]
	v_pk_mul_f32 v[0:1], v[6:7], v[194:195] op_sel:[0,1] op_sel_hi:[1,0]
	v_pk_mul_f32 v[2:3], v[6:7], v[118:119] op_sel:[0,1] op_sel_hi:[1,0]
	v_xor_b32_e32 v6, 0x80000000, v9
	v_mov_b32_e32 v7, v9
	v_pk_fma_f32 v[0:1], v[4:5], v[194:195], v[0:1] op_sel_hi:[0,1,1]
	v_pk_fma_f32 v[4:5], v[4:5], v[118:119], v[2:3] op_sel_hi:[0,1,1]
	v_pk_mul_f32 v[2:3], v[140:141], v[6:7] op_sel:[1,0] op_sel_hi:[0,1]
	v_pk_mul_f32 v[6:7], v[6:7], v[18:19] op_sel:[0,1] op_sel_hi:[1,0]
	v_pk_fma_f32 v[2:3], v[140:141], v[8:9], v[2:3] op_sel_hi:[1,0,1]
	v_pk_fma_f32 v[6:7], v[8:9], v[18:19], v[6:7] op_sel_hi:[0,1,1]
	ds_write_b128 v165, v[0:3] offset:16
	ds_write_b128 v166, v[4:7] offset:16
	ds_read_b64 v[0:1], v197
	s_waitcnt lgkmcnt(0)
	v_xor_b32_e32 v2, 0x80000000, v1
	v_mov_b32_e32 v3, v1
	v_pk_mul_f32 v[4:5], v[0:1], v[2:3] op_sel:[1,0] op_sel_hi:[0,1]
	v_pk_fma_f32 v[4:5], v[0:1], v[0:1], v[4:5] op_sel_hi:[1,0,1]
	v_pk_mul_f32 v[6:7], v[2:3], v[112:113] op_sel:[0,1] op_sel_hi:[1,0]
	v_pk_mul_f32 v[8:9], v[2:3], v[22:23] op_sel:[0,1] op_sel_hi:[1,0]
	v_pk_mul_f32 v[2:3], v[2:3], v[4:5] op_sel:[0,1] op_sel_hi:[1,0]
	v_pk_fma_f32 v[18:19], v[0:1], v[112:113], v[6:7] op_sel_hi:[0,1,1]
	v_pk_fma_f32 v[22:23], v[0:1], v[22:23], v[8:9] op_sel_hi:[0,1,1]
	v_xor_b32_e32 v6, 0x80000000, v5
	v_mov_b32_e32 v7, v5
	v_pk_fma_f32 v[8:9], v[0:1], v[4:5], v[2:3] op_sel_hi:[0,1,1]
	v_pk_mul_f32 v[0:1], v[6:7], v[116:117] op_sel:[0,1] op_sel_hi:[1,0]
	v_pk_mul_f32 v[2:3], v[6:7], v[136:137] op_sel:[0,1] op_sel_hi:[1,0]
	v_xor_b32_e32 v6, 0x80000000, v9
	v_mov_b32_e32 v7, v9
	v_pk_fma_f32 v[0:1], v[4:5], v[116:117], v[0:1] op_sel_hi:[0,1,1]
	v_pk_fma_f32 v[4:5], v[4:5], v[136:137], v[2:3] op_sel_hi:[0,1,1]
	v_pk_mul_f32 v[2:3], v[138:139], v[6:7] op_sel:[1,0] op_sel_hi:[0,1]
	v_pk_mul_f32 v[6:7], v[6:7], v[122:123] op_sel:[0,1] op_sel_hi:[1,0]
	v_pk_fma_f32 v[2:3], v[138:139], v[8:9], v[2:3] op_sel_hi:[1,0,1]
	ds_write_b128 v167, v[16:19]
	ds_write_b128 v168, v[20:23]
	v_pk_fma_f32 v[6:7], v[8:9], v[122:123], v[6:7] op_sel_hi:[0,1,1]
	ds_write_b128 v167, v[0:3] offset:16
	ds_write_b128 v168, v[4:7] offset:16
	ds_read_b64 v[0:1], v198
	s_waitcnt lgkmcnt(0)
	v_xor_b32_e32 v2, 0x80000000, v1
	v_mov_b32_e32 v3, v1
	v_pk_mul_f32 v[4:5], v[0:1], v[2:3] op_sel:[1,0] op_sel_hi:[0,1]
	v_pk_fma_f32 v[4:5], v[0:1], v[0:1], v[4:5] op_sel_hi:[1,0,1]
	v_pk_mul_f32 v[6:7], v[2:3], v[132:133] op_sel:[0,1] op_sel_hi:[1,0]
	v_pk_mul_f32 v[8:9], v[2:3], v[190:191] op_sel:[0,1] op_sel_hi:[1,0]
	v_pk_mul_f32 v[2:3], v[2:3], v[4:5] op_sel:[0,1] op_sel_hi:[1,0]
	v_pk_fma_f32 v[26:27], v[0:1], v[132:133], v[6:7] op_sel_hi:[0,1,1]
	v_pk_fma_f32 v[30:31], v[0:1], v[190:191], v[8:9] op_sel_hi:[0,1,1]
	v_xor_b32_e32 v6, 0x80000000, v5
	v_mov_b32_e32 v7, v5
	v_pk_fma_f32 v[8:9], v[0:1], v[4:5], v[2:3] op_sel_hi:[0,1,1]
	v_pk_mul_f32 v[0:1], v[6:7], v[134:135] op_sel:[0,1] op_sel_hi:[1,0]
	v_pk_mul_f32 v[2:3], v[6:7], v[124:125] op_sel:[0,1] op_sel_hi:[1,0]
	v_xor_b32_e32 v6, 0x80000000, v9
	v_mov_b32_e32 v7, v9
	v_pk_fma_f32 v[0:1], v[4:5], v[134:135], v[0:1] op_sel_hi:[0,1,1]
	v_pk_fma_f32 v[4:5], v[4:5], v[124:125], v[2:3] op_sel_hi:[0,1,1]
	v_pk_mul_f32 v[2:3], v[188:189], v[6:7] op_sel:[1,0] op_sel_hi:[0,1]
	v_pk_mul_f32 v[6:7], v[6:7], v[114:115] op_sel:[0,1] op_sel_hi:[1,0]
	v_pk_fma_f32 v[2:3], v[188:189], v[8:9], v[2:3] op_sel_hi:[1,0,1]
	ds_write_b128 v169, v[24:27]
	ds_write_b128 v170, v[28:31]
	v_pk_fma_f32 v[6:7], v[8:9], v[114:115], v[6:7] op_sel_hi:[0,1,1]
	ds_write_b128 v169, v[0:3] offset:16
	ds_write_b128 v170, v[4:7] offset:16
	s_waitcnt lgkmcnt(0)
	s_barrier
	s_cbranch_scc0 .LBB0_1393
	ds_read2st64_b64 v[0:3], v145 offset1:8
	ds_read2st64_b64 v[4:7], v145 offset0:64 offset1:72
	ds_read_b64 v[118:119], v33
	ds_read_b64 v[120:121], v146
	ds_read_b64 v[122:123], v148
	ds_read_b64 v[124:125], v149
	ds_read2st64_b64 v[8:11], v145 offset0:16 offset1:24
	ds_read2st64_b64 v[12:15], v145 offset0:80 offset1:88
	ds_read_b64 v[126:127], v151
	ds_read_b64 v[128:129], v152
	ds_read_b64 v[130:131], v154
	ds_read_b64 v[132:133], v155
	ds_read2st64_b64 v[16:19], v145 offset0:32 offset1:40
	ds_read2st64_b64 v[20:23], v145 offset0:96 offset1:104
	ds_read_b64 v[134:135], v156
	ds_read_b64 v[136:137], v157
	ds_read_b64 v[138:139], v158
	ds_read_b64 v[140:141], v159
	ds_read2st64_b64 v[24:27], v145 offset0:48 offset1:56
	ds_read2st64_b64 v[28:31], v145 offset0:112 offset1:120
	ds_read_b64 v[142:143], v160
	ds_read_b64 v[184:185], v161
	ds_read_b64 v[186:187], v162
	ds_read_b64 v[188:189], v163
	s_waitcnt lgkmcnt(14)
	v_pk_add_f32 v[112:113], v[0:1], v[4:5]
	v_pk_add_f32 v[114:115], v[0:1], v[4:5] neg_lo:[0,1] neg_hi:[0,1]
	v_pk_add_f32 v[0:1], v[2:3], v[6:7]
	v_pk_add_f32 v[2:3], v[2:3], v[6:7] neg_lo:[0,1] neg_hi:[0,1]
	s_waitcnt lgkmcnt(0)
	s_barrier
	v_pk_add_f32 v[116:117], v[118:119], v[120:121]
	v_pk_add_f32 v[118:119], v[118:119], v[120:121] neg_lo:[0,1] neg_hi:[0,1]
	ds_write_b128 v171, v[112:115]
	ds_write_b128 v172, v[116:119]
	v_pk_add_f32 v[4:5], v[122:123], v[124:125]
	v_pk_add_f32 v[6:7], v[122:123], v[124:125] neg_lo:[0,1] neg_hi:[0,1]
	ds_write_b128 v171, v[0:3] offset:8192
	ds_write_b128 v173, v[4:7]
	v_pk_add_f32 v[0:1], v[8:9], v[12:13]
	v_pk_add_f32 v[2:3], v[8:9], v[12:13] neg_lo:[0,1] neg_hi:[0,1]
	v_pk_add_f32 v[4:5], v[126:127], v[128:129]
	v_pk_add_f32 v[6:7], v[126:127], v[128:129] neg_lo:[0,1] neg_hi:[0,1]
	ds_write_b128 v171, v[0:3] offset:16384
	ds_write_b128 v174, v[4:7]
	v_pk_add_f32 v[0:1], v[10:11], v[14:15]
	v_pk_add_f32 v[2:3], v[10:11], v[14:15] neg_lo:[0,1] neg_hi:[0,1]
	v_pk_add_f32 v[4:5], v[130:131], v[132:133]
	v_pk_add_f32 v[6:7], v[130:131], v[132:133] neg_lo:[0,1] neg_hi:[0,1]
	ds_write_b128 v171, v[0:3] offset:24576
	ds_write_b128 v175, v[4:7]
	v_pk_add_f32 v[0:1], v[16:17], v[20:21]
	v_pk_add_f32 v[2:3], v[16:17], v[20:21] neg_lo:[0,1] neg_hi:[0,1]
	v_pk_add_f32 v[4:5], v[134:135], v[136:137]
	v_pk_add_f32 v[6:7], v[134:135], v[136:137] neg_lo:[0,1] neg_hi:[0,1]
	ds_write_b128 v171, v[0:3] offset:32768
	ds_write_b128 v176, v[4:7]
	v_pk_add_f32 v[0:1], v[18:19], v[22:23]
	v_pk_add_f32 v[2:3], v[18:19], v[22:23] neg_lo:[0,1] neg_hi:[0,1]
	v_pk_add_f32 v[4:5], v[138:139], v[140:141]
	v_pk_add_f32 v[6:7], v[138:139], v[140:141] neg_lo:[0,1] neg_hi:[0,1]
	ds_write_b128 v171, v[0:3] offset:40960
	ds_write_b128 v177, v[4:7]
	v_pk_add_f32 v[0:1], v[24:25], v[28:29]
	v_pk_add_f32 v[2:3], v[24:25], v[28:29] neg_lo:[0,1] neg_hi:[0,1]
	v_pk_add_f32 v[4:5], v[142:143], v[184:185]
	v_pk_add_f32 v[6:7], v[142:143], v[184:185] neg_lo:[0,1] neg_hi:[0,1]
	ds_write_b128 v171, v[0:3] offset:49152
	ds_write_b128 v178, v[4:7]
	v_pk_add_f32 v[0:1], v[26:27], v[30:31]
	v_pk_add_f32 v[2:3], v[26:27], v[30:31] neg_lo:[0,1] neg_hi:[0,1]
	v_pk_add_f32 v[4:5], v[186:187], v[188:189]
	v_pk_add_f32 v[6:7], v[186:187], v[188:189] neg_lo:[0,1] neg_hi:[0,1]
	ds_write_b128 v171, v[0:3] offset:57344
	ds_write_b128 v179, v[4:7]
	v_and_b32_e32 v2, 0xff, v32
	v_lshrrev_b32_e32 v0, 8, v32
	v_lshlrev_b32_e32 v2, 1, v2
	v_lshl_or_b32 v2, v0, 12, v2
	s_waitcnt lgkmcnt(0)
	s_barrier
	s_mov_b32 s40, 0
	v_lshlrev_b32_e32 v3, 5, v2
	v_lshlrev_b32_e32 v4, 9, v2
	v_lshlrev_b32_e32 v5, 12, v2
	v_lshrrev_b32_e32 v0, 3, v2
	v_lshlrev_b32_e32 v1, 1, v2
	v_and_b32_e32 v3, 0x300, v3
	v_and_b32_e32 v4, 0xc00, v4
	v_and_b32_e32 v5, 0x1000, v5
	v_and_b32_e32 v0, 48, v0
	v_and_b32_e32 v1, 0xc0, v1
	v_or3_b32 v3, v4, v5, v3
	v_or3_b32 v3, v3, v1, v0
	v_lshl_add_u32 v4, v2, 3, 0
	s_branch .LBB0_1396
.LBB0_1395:
	s_or_b64 exec, exec, s[4:5]
	s_addk_i32 s40, 0x2000
	s_cmp_eq_u32 s40, 0x8000
	v_add_u32_e32 v2, 0x400, v2
	s_cbranch_scc1 .Lfft_k4096
	s_cmp_eq_u32 s40, 0x22000
	s_cbranch_scc1 .LBB0_1410

.Lfft_k4096:
	s_mov_b32 s40, 0x20000
	v_cmp_eq_u32_e32 vcc, 0, v32
	s_nop 1
	v_cndmask_b32_e64 v2, 3, 1, vcc
	v_lshlrev_b32_e32 v3, 5, v2
	v_lshlrev_b32_e32 v4, 9, v2
	v_lshlrev_b32_e32 v5, 12, v2
	v_lshrrev_b32_e32 v0, 3, v2
	v_lshlrev_b32_e32 v1, 1, v2
	v_and_b32_e32 v3, 0x300, v3
	v_and_b32_e32 v4, 0xc00, v4
	v_and_b32_e32 v5, 0x1000, v5
	v_and_b32_e32 v0, 48, v0
	v_and_b32_e32 v1, 0xc0, v1
	v_or3_b32 v3, v4, v5, v3
	v_or3_b32 v3, v3, v1, v0
	v_lshlrev_b32_e32 v4, 3, v2
	v_add_u32_e32 v4, 0xfffe0000, v4
	s_branch .LBB0_1396
